# causal-mask blocks of the diagonal tiles: row-keybase computed once, per score one v_cmp_le of an inline constant into one of three rotating SGPR pairs + one v_cndmask (no wait states)
# baseline (speedup 1.0000x reference)
.Lmla_a_mask:
	v_add_u32_e32 v0, s54, v161
	v_sub_u32_e32 v122, v159, v0
	v_cmp_le_i32_e32 vcc, 32, v122
	v_cmp_le_i32_e64 s[98:99], 1, v122
	v_cmp_le_i32_e64 s[100:101], 0, v122
	v_cndmask_b32_e32 v50, v149, v50, vcc
	v_cndmask_b32_e64 v35, v149, v35, s[98:99]
	v_cndmask_b32_e64 v34, v149, v34, s[100:101]
	v_cmp_le_i32_e32 vcc, 33, v122
	v_cmp_le_i32_e64 s[98:99], 2, v122
	v_cmp_le_i32_e64 s[100:101], 34, v122
	v_cndmask_b32_e32 v51, v149, v51, vcc
	v_cndmask_b32_e64 v36, v149, v36, s[98:99]
	v_cndmask_b32_e64 v52, v149, v52, s[100:101]
	v_cmp_le_i32_e32 vcc, 3, v122
	v_cmp_le_i32_e64 s[98:99], 35, v122
	v_cmp_le_i32_e64 s[100:101], 8, v122
	v_cndmask_b32_e32 v37, v149, v37, vcc
	v_cndmask_b32_e64 v53, v149, v53, s[98:99]
	v_cndmask_b32_e64 v38, v149, v38, s[100:101]
	v_cmp_le_i32_e32 vcc, 40, v122
	v_cmp_le_i32_e64 s[98:99], 9, v122
	v_cmp_le_i32_e64 s[100:101], 41, v122
	v_cndmask_b32_e32 v54, v149, v54, vcc
	v_cndmask_b32_e64 v39, v149, v39, s[98:99]
	v_cndmask_b32_e64 v55, v149, v55, s[100:101]
	v_cmp_le_i32_e32 vcc, 10, v122
	v_cmp_le_i32_e64 s[98:99], 42, v122
	v_cmp_le_i32_e64 s[100:101], 11, v122
	v_cndmask_b32_e32 v40, v149, v40, vcc
	v_cndmask_b32_e64 v56, v149, v56, s[98:99]
	v_cndmask_b32_e64 v41, v149, v41, s[100:101]
	v_cmp_le_i32_e32 vcc, 43, v122
	v_cmp_le_i32_e64 s[98:99], 16, v122
	v_cmp_le_i32_e64 s[100:101], 48, v122
	v_cndmask_b32_e32 v57, v149, v57, vcc
	v_cndmask_b32_e64 v42, v149, v42, s[98:99]
	v_cndmask_b32_e64 v58, v149, v58, s[100:101]
	v_cmp_le_i32_e32 vcc, 17, v122
	v_cmp_le_i32_e64 s[98:99], 49, v122
	v_cmp_le_i32_e64 s[100:101], 18, v122
	v_cndmask_b32_e32 v43, v149, v43, vcc
	v_cndmask_b32_e64 v59, v149, v59, s[98:99]
	v_cndmask_b32_e64 v44, v149, v44, s[100:101]
	v_cmp_le_i32_e32 vcc, 50, v122
	v_cmp_le_i32_e64 s[98:99], 19, v122
	v_cmp_le_i32_e64 s[100:101], 51, v122
	v_cndmask_b32_e32 v60, v149, v60, vcc
	v_cndmask_b32_e64 v45, v149, v45, s[98:99]
	v_cndmask_b32_e64 v61, v149, v61, s[100:101]
	v_cmp_le_i32_e32 vcc, 24, v122
	v_cmp_le_i32_e64 s[98:99], 56, v122
	v_cmp_le_i32_e64 s[100:101], 25, v122
	v_cndmask_b32_e32 v46, v149, v46, vcc
	v_cndmask_b32_e64 v62, v149, v62, s[98:99]
	v_cndmask_b32_e64 v47, v149, v47, s[100:101]
	v_cmp_le_i32_e32 vcc, 57, v122
	v_cmp_le_i32_e64 s[98:99], 26, v122
	v_cmp_le_i32_e64 s[100:101], 58, v122
	v_cndmask_b32_e32 v63, v149, v63, vcc
	v_cndmask_b32_e64 v48, v149, v48, s[98:99]
	v_cndmask_b32_e64 v64, v149, v64, s[100:101]
	v_cmp_le_i32_e32 vcc, 27, v122
	v_cmp_le_i32_e64 s[98:99], 59, v122
	s_nop 0
	v_cndmask_b32_e32 v49, v149, v49, vcc
	v_cndmask_b32_e64 v65, v149, v65, s[98:99]
	s_branch .LBB0_1040

.Lmla_b_mask:
	v_add_u32_e32 v0, s54, v161
	v_sub_u32_e32 v107, v159, v0
	v_add_u32_e32 v107, 0xffffffc0, v107
	v_cmp_le_i32_e32 vcc, 32, v107
	v_cmp_le_i32_e64 s[98:99], 1, v107
	v_cmp_le_i32_e64 s[100:101], 0, v107
	v_cndmask_b32_e32 v50, v149, v50, vcc
	v_cndmask_b32_e64 v35, v149, v35, s[98:99]
	v_cndmask_b32_e64 v34, v149, v34, s[100:101]
	v_cmp_le_i32_e32 vcc, 33, v107
	v_cmp_le_i32_e64 s[98:99], 2, v107
	v_cmp_le_i32_e64 s[100:101], 34, v107
	v_cndmask_b32_e32 v51, v149, v51, vcc
	v_cndmask_b32_e64 v36, v149, v36, s[98:99]
	v_cndmask_b32_e64 v52, v149, v52, s[100:101]
	v_cmp_le_i32_e32 vcc, 3, v107
	v_cmp_le_i32_e64 s[98:99], 35, v107
	v_cmp_le_i32_e64 s[100:101], 8, v107
	v_cndmask_b32_e32 v37, v149, v37, vcc
	v_cndmask_b32_e64 v53, v149, v53, s[98:99]
	v_cndmask_b32_e64 v38, v149, v38, s[100:101]
	v_cmp_le_i32_e32 vcc, 40, v107
	v_cmp_le_i32_e64 s[98:99], 9, v107
	v_cmp_le_i32_e64 s[100:101], 41, v107
	v_cndmask_b32_e32 v54, v149, v54, vcc
	v_cndmask_b32_e64 v39, v149, v39, s[98:99]
	v_cndmask_b32_e64 v55, v149, v55, s[100:101]
	v_cmp_le_i32_e32 vcc, 10, v107
	v_cmp_le_i32_e64 s[98:99], 42, v107
	v_cmp_le_i32_e64 s[100:101], 11, v107
	v_cndmask_b32_e32 v40, v149, v40, vcc
	v_cndmask_b32_e64 v56, v149, v56, s[98:99]
	v_cndmask_b32_e64 v41, v149, v41, s[100:101]
	v_cmp_le_i32_e32 vcc, 43, v107
	v_cmp_le_i32_e64 s[98:99], 16, v107
	v_cmp_le_i32_e64 s[100:101], 48, v107
	v_cndmask_b32_e32 v57, v149, v57, vcc
	v_cndmask_b32_e64 v42, v149, v42, s[98:99]
	v_cndmask_b32_e64 v58, v149, v58, s[100:101]
	v_cmp_le_i32_e32 vcc, 17, v107
	v_cmp_le_i32_e64 s[98:99], 49, v107
	v_cmp_le_i32_e64 s[100:101], 18, v107
	v_cndmask_b32_e32 v43, v149, v43, vcc
	v_cndmask_b32_e64 v59, v149, v59, s[98:99]
	v_cndmask_b32_e64 v44, v149, v44, s[100:101]
	v_cmp_le_i32_e32 vcc, 50, v107
	v_cmp_le_i32_e64 s[98:99], 19, v107
	v_cmp_le_i32_e64 s[100:101], 51, v107
	v_cndmask_b32_e32 v60, v149, v60, vcc
	v_cndmask_b32_e64 v45, v149, v45, s[98:99]
	v_cndmask_b32_e64 v61, v149, v61, s[100:101]
	v_cmp_le_i32_e32 vcc, 24, v107
	v_cmp_le_i32_e64 s[98:99], 56, v107
	v_cmp_le_i32_e64 s[100:101], 25, v107
	v_cndmask_b32_e32 v46, v149, v46, vcc
	v_cndmask_b32_e64 v62, v149, v62, s[98:99]
	v_cndmask_b32_e64 v47, v149, v47, s[100:101]
	v_cmp_le_i32_e32 vcc, 57, v107
	v_cmp_le_i32_e64 s[98:99], 26, v107
	v_cmp_le_i32_e64 s[100:101], 58, v107
	v_cndmask_b32_e32 v63, v149, v63, vcc
	v_cndmask_b32_e64 v48, v149, v48, s[98:99]
	v_cndmask_b32_e64 v64, v149, v64, s[100:101]
	v_cmp_le_i32_e32 vcc, 27, v107
	v_cmp_le_i32_e64 s[98:99], 59, v107
	s_nop 0
	v_cndmask_b32_e32 v49, v149, v49, vcc
	v_cndmask_b32_e64 v65, v149, v65, s[98:99]
	s_branch .LBB0_1056

.Ldiff_a_mask:
	v_add_u32_e32 v0, s47, v194
	v_sub_u32_e32 v14, v192, v0
	v_cmp_le_i32_e32 vcc, 32, v14
	v_cmp_le_i32_e64 s[98:99], 1, v14
	v_cmp_le_i32_e64 s[100:101], 0, v14
	v_cndmask_b32_e32 v96, v185, v96, vcc
	v_cndmask_b32_e64 v81, v185, v81, s[98:99]
	v_cndmask_b32_e64 v80, v185, v80, s[100:101]
	v_cmp_le_i32_e32 vcc, 33, v14
	v_cmp_le_i32_e64 s[98:99], 2, v14
	v_cmp_le_i32_e64 s[100:101], 34, v14
	v_cndmask_b32_e32 v97, v185, v97, vcc
	v_cndmask_b32_e64 v82, v185, v82, s[98:99]
	v_cndmask_b32_e64 v98, v185, v98, s[100:101]
	v_cmp_le_i32_e32 vcc, 3, v14
	v_cmp_le_i32_e64 s[98:99], 35, v14
	v_cmp_le_i32_e64 s[100:101], 8, v14
	v_cndmask_b32_e32 v83, v185, v83, vcc
	v_cndmask_b32_e64 v99, v185, v99, s[98:99]
	v_cndmask_b32_e64 v84, v185, v84, s[100:101]
	v_cmp_le_i32_e32 vcc, 40, v14
	v_cmp_le_i32_e64 s[98:99], 9, v14
	v_cmp_le_i32_e64 s[100:101], 41, v14
	v_cndmask_b32_e32 v100, v185, v100, vcc
	v_cndmask_b32_e64 v85, v185, v85, s[98:99]
	v_cndmask_b32_e64 v101, v185, v101, s[100:101]
	v_cmp_le_i32_e32 vcc, 10, v14
	v_cmp_le_i32_e64 s[98:99], 42, v14
	v_cmp_le_i32_e64 s[100:101], 11, v14
	v_cndmask_b32_e32 v86, v185, v86, vcc
	v_cndmask_b32_e64 v102, v185, v102, s[98:99]
	v_cndmask_b32_e64 v87, v185, v87, s[100:101]
	v_cmp_le_i32_e32 vcc, 43, v14
	v_cmp_le_i32_e64 s[98:99], 16, v14
	v_cmp_le_i32_e64 s[100:101], 48, v14
	v_cndmask_b32_e32 v103, v185, v103, vcc
	v_cndmask_b32_e64 v88, v185, v88, s[98:99]
	v_cndmask_b32_e64 v104, v185, v104, s[100:101]
	v_cmp_le_i32_e32 vcc, 17, v14
	v_cmp_le_i32_e64 s[98:99], 49, v14
	v_cmp_le_i32_e64 s[100:101], 18, v14
	v_cndmask_b32_e32 v89, v185, v89, vcc
	v_cndmask_b32_e64 v105, v185, v105, s[98:99]
	v_cndmask_b32_e64 v90, v185, v90, s[100:101]
	v_cmp_le_i32_e32 vcc, 50, v14
	v_cmp_le_i32_e64 s[98:99], 19, v14
	v_cmp_le_i32_e64 s[100:101], 51, v14
	v_cndmask_b32_e32 v106, v185, v106, vcc
	v_cndmask_b32_e64 v91, v185, v91, s[98:99]
	v_cndmask_b32_e64 v107, v185, v107, s[100:101]
	v_cmp_le_i32_e32 vcc, 24, v14
	v_cmp_le_i32_e64 s[98:99], 56, v14
	v_cmp_le_i32_e64 s[100:101], 25, v14
	v_cndmask_b32_e32 v92, v185, v92, vcc
	v_cndmask_b32_e64 v108, v185, v108, s[98:99]
	v_cndmask_b32_e64 v93, v185, v93, s[100:101]
	v_cmp_le_i32_e32 vcc, 57, v14
	v_cmp_le_i32_e64 s[98:99], 26, v14
	v_cmp_le_i32_e64 s[100:101], 58, v14
	v_cndmask_b32_e32 v109, v185, v109, vcc
	v_cndmask_b32_e64 v94, v185, v94, s[98:99]
	v_cndmask_b32_e64 v110, v185, v110, s[100:101]
	v_cmp_le_i32_e32 vcc, 27, v14
	v_cmp_le_i32_e64 s[98:99], 59, v14
	s_nop 0
	v_cndmask_b32_e32 v95, v185, v95, vcc
	v_cndmask_b32_e64 v111, v185, v111, s[98:99]
	s_branch .LBB0_1075

.Ldiff_b_mask:
	v_add_u32_e32 v14, s47, v194
	v_sub_u32_e32 v140, v192, v14
	v_add_u32_e32 v140, 0xffffffc0, v140
	v_cmp_le_i32_e32 vcc, 32, v140
	v_cmp_le_i32_e64 s[98:99], 1, v140
	v_cmp_le_i32_e64 s[100:101], 0, v140
	v_cndmask_b32_e32 v96, v185, v96, vcc
	v_cndmask_b32_e64 v81, v185, v81, s[98:99]
	v_cndmask_b32_e64 v80, v185, v80, s[100:101]
	v_cmp_le_i32_e32 vcc, 33, v140
	v_cmp_le_i32_e64 s[98:99], 2, v140
	v_cmp_le_i32_e64 s[100:101], 34, v140
	v_cndmask_b32_e32 v97, v185, v97, vcc
	v_cndmask_b32_e64 v82, v185, v82, s[98:99]
	v_cndmask_b32_e64 v98, v185, v98, s[100:101]
	v_cmp_le_i32_e32 vcc, 3, v140
	v_cmp_le_i32_e64 s[98:99], 35, v140
	v_cmp_le_i32_e64 s[100:101], 8, v140
	v_cndmask_b32_e32 v83, v185, v83, vcc
	v_cndmask_b32_e64 v99, v185, v99, s[98:99]
	v_cndmask_b32_e64 v84, v185, v84, s[100:101]
	v_cmp_le_i32_e32 vcc, 40, v140
	v_cmp_le_i32_e64 s[98:99], 9, v140
	v_cmp_le_i32_e64 s[100:101], 41, v140
	v_cndmask_b32_e32 v100, v185, v100, vcc
	v_cndmask_b32_e64 v85, v185, v85, s[98:99]
	v_cndmask_b32_e64 v101, v185, v101, s[100:101]
	v_cmp_le_i32_e32 vcc, 10, v140
	v_cmp_le_i32_e64 s[98:99], 42, v140
	v_cmp_le_i32_e64 s[100:101], 11, v140
	v_cndmask_b32_e32 v86, v185, v86, vcc
	v_cndmask_b32_e64 v102, v185, v102, s[98:99]
	v_cndmask_b32_e64 v87, v185, v87, s[100:101]
	v_cmp_le_i32_e32 vcc, 43, v140
	v_cmp_le_i32_e64 s[98:99], 16, v140
	v_cmp_le_i32_e64 s[100:101], 48, v140
	v_cndmask_b32_e32 v103, v185, v103, vcc
	v_cndmask_b32_e64 v88, v185, v88, s[98:99]
	v_cndmask_b32_e64 v104, v185, v104, s[100:101]
	v_cmp_le_i32_e32 vcc, 17, v140
	v_cmp_le_i32_e64 s[98:99], 49, v140
	v_cmp_le_i32_e64 s[100:101], 18, v140
	v_cndmask_b32_e32 v89, v185, v89, vcc
	v_cndmask_b32_e64 v105, v185, v105, s[98:99]
	v_cndmask_b32_e64 v90, v185, v90, s[100:101]
	v_cmp_le_i32_e32 vcc, 50, v140
	v_cmp_le_i32_e64 s[98:99], 19, v140
	v_cmp_le_i32_e64 s[100:101], 51, v140
	v_cndmask_b32_e32 v106, v185, v106, vcc
	v_cndmask_b32_e64 v91, v185, v91, s[98:99]
	v_cndmask_b32_e64 v107, v185, v107, s[100:101]
	v_cmp_le_i32_e32 vcc, 24, v140
	v_cmp_le_i32_e64 s[98:99], 56, v140
	v_cmp_le_i32_e64 s[100:101], 25, v140
	v_cndmask_b32_e32 v92, v185, v92, vcc
	v_cndmask_b32_e64 v108, v185, v108, s[98:99]
	v_cndmask_b32_e64 v93, v185, v93, s[100:101]
	v_cmp_le_i32_e32 vcc, 57, v140
	v_cmp_le_i32_e64 s[98:99], 26, v140
	v_cmp_le_i32_e64 s[100:101], 58, v140
	v_cndmask_b32_e32 v109, v185, v109, vcc
	v_cndmask_b32_e64 v94, v185, v94, s[98:99]
	v_cndmask_b32_e64 v110, v185, v110, s[100:101]
	v_cmp_le_i32_e32 vcc, 27, v140
	v_cmp_le_i32_e64 s[98:99], 59, v140
	s_nop 0
	v_cndmask_b32_e32 v95, v185, v95, vcc
	v_cndmask_b32_e64 v111, v185, v111, s[98:99]
	s_branch .LBB0_1091
